# RESID epilogue first-layer path: the f32 input residual loaded in two batches of 16 loads instead of 2 loads + wait per half-step
# speedup vs baseline: 1.0081x; 1.0081x over previous
; #define PG8_STAGE(bufoff, gbase, voff) do { _Pragma("unroll") for (int _i = 0; _i < 2; ++_i) \
;     __builtin_amdgcn_global_load_lds((const unsigned*)((const char*)(gbase) + (voff)[_i]), (LAS unsigned*)(lds + (bufoff) + ldsw + _i * 8192), 16, 0, 0); } while (0)
; #define PG8_LDA(dst, b, h) do { _Pragma("unroll") for (int m = 0; m < 4; ++m) _Pragma("unroll") for (int k = 0; k < 2; ++k) dst[m][k] = *(const LAS bf16x8*)(lds + PG8_SA(b, h) + aoff + m * 2048 + k * 1024); } while (0)
; #define PG8_LDB(dst, b, h) do { _Pragma("unroll") for (int n = 0; n < 2; ++n) _Pragma("unroll") for (int k = 0; k < 2; ++k) dst[n][k] = *(const LAS bf16x8*)(lds + PG8_SB(b, h) + boff + n * 2048 + k * 1024); } while (0)
; #define PG8_MMA(ai, bj, At, Bt) do { __builtin_amdgcn_s_setprio(1); _Pragma("unroll") for (int m = 0; m < 4; ++m) _Pragma("unroll") for (int n = 0; n < 2; ++n) _Pragma("unroll") for (int k = 0; k < 2; ++k) \
;     acc[ai][bj][m][n] = __builtin_amdgcn_mfma_f32_16x16x32_bf16(Bt[n][k], At[m][k], acc[ai][bj][m][n], 0, 0, 0); __builtin_amdgcn_s_setprio(0); } while (0)
; #define PG8_WAIT_V(n) asm volatile("s_waitcnt vmcnt(" #n ")" ::: "memory")
; #define PG8_WAIT_L(n) asm volatile("s_waitcnt lgkmcnt(" #n ")" ::: "memory")
; #define PG8_BAR __builtin_amdgcn_s_barrier()
; #define PG8_SCHED __builtin_amdgcn_sched_barrier(0)
; template <class Epi, class Sched>
; DI void gemm_phase(LAS unsigned char* lds, const Gemm g, const Sched& S, const Epi& E) {
;     ...
;     for (int t = 0; t < nt; t += 2) {
;       const bool last = (t == nt - 2);
;       const char* a1 = cA + (size_t)(t + 1) * kstep;
;       const char* a2 = last ? nA : cA + (size_t)(t + 2) * kstep; const char* b2 = last ? nB : cB + (size_t)(t + 2) * kstep;
;       const char* a3 = a2 + kstep; const char* b3 = b2 + kstep;
;       PG8_LDB(B0, 0, 0); PG8_SCHED; PG8_LDA(At, 0, 0); PG8_STAGE(PG8_SA(1, 1), a1 + hstep, voffA);
;       PG8_WAIT_L(8); PG8_BAR; PG8_WAIT_L(0); PG8_MMA(0, 0, At, B0); PG8_BAR; PG8_SCHED;
;       PG8_LDB(B1, 0, 1); PG8_STAGE(PG8_SB(0, 0), b2, voffB);
;       PG8_BAR; PG8_WAIT_L(0); PG8_MMA(0, 1, At, B1); PG8_BAR;
;       PG8_LDA(At, 0, 1); PG8_STAGE(PG8_SA(0, 0), a2, voffA);
;       PG8_BAR; PG8_WAIT_L(0); PG8_MMA(1, 0, At, B0); PG8_BAR; PG8_SCHED;
;       PG8_STAGE(PG8_SB(0, 1), b2 + hstep, voffB);
;       PG8_WAIT_V(6); PG8_BAR; PG8_MMA(1, 1, At, B1); PG8_BAR;
.LBB0_1644:
	s_add_u32 s4, s2, 0xfffc0080
	s_addc_u32 s5, s3, -1
	s_add_i32 s55, 0, 0x10000
	ds_read_b128 v[128:131], v224
	ds_read_b128 v[132:135], v224 offset:1024
	ds_read_b128 v[148:151], v224 offset:2048
	ds_read_b128 v[152:155], v224 offset:3072
	s_cmp_eq_u32 s54, 12
	s_cselect_b32 s29, s19, s5
	s_cselect_b32 s28, s35, s4
	s_cselect_b32 s5, s17, s53
	s_cselect_b32 s4, s51, s52
	s_add_i32 m0, s41, 0xc000
	ds_read_b128 v[160:163], v159
	ds_read_b128 v[164:167], v159 offset:1024
	ds_read_b128 v[168:171], v159 offset:2048
	ds_read_b128 v[172:175], v159 offset:3072
	ds_read_b128 v[176:179], v159 offset:4096
	ds_read_b128 v[196:199], v159 offset:5120
	ds_read_b128 v[200:203], v159 offset:6144
	ds_read_b128 v[204:207], v159 offset:7168
	global_load_lds_dwordx4 v142, s[2:3]
	s_add_i32 m0, s41, 0xe000
	s_nop 0
	global_load_lds_dwordx4 v146, s[2:3]
	s_waitcnt lgkmcnt(8)
	s_barrier
	s_waitcnt lgkmcnt(0)
	v_mfma_f32_16x16x32_bf16 v[124:127], v[128:131], v[160:163], v[124:127]
	v_mfma_f32_16x16x32_bf16 v[120:123], v[148:151], v[160:163], v[120:123]
	v_mfma_f32_16x16x32_bf16 v[108:111], v[128:131], v[168:171], v[108:111]
	v_mfma_f32_16x16x32_bf16 v[104:107], v[148:151], v[168:171], v[104:107]
	v_mfma_f32_16x16x32_bf16 v[92:95], v[128:131], v[176:179], v[92:95]
	v_mfma_f32_16x16x32_bf16 v[88:91], v[148:151], v[176:179], v[88:91]
	v_mfma_f32_16x16x32_bf16 v[76:79], v[128:131], v[200:203], v[76:79]
	v_mfma_f32_16x16x32_bf16 v[72:75], v[148:151], v[200:203], v[72:75]
	v_mfma_f32_16x16x32_bf16 v[124:127], v[132:135], v[164:167], v[124:127]
	v_mfma_f32_16x16x32_bf16 v[120:123], v[152:155], v[164:167], v[120:123]
	v_mfma_f32_16x16x32_bf16 v[108:111], v[132:135], v[172:175], v[108:111]
	v_mfma_f32_16x16x32_bf16 v[104:107], v[152:155], v[172:175], v[104:107]
	v_mfma_f32_16x16x32_bf16 v[92:95], v[132:135], v[196:199], v[92:95]
	v_mfma_f32_16x16x32_bf16 v[88:91], v[152:155], v[196:199], v[88:91]
	v_mfma_f32_16x16x32_bf16 v[76:79], v[132:135], v[204:207], v[76:79]
	v_mfma_f32_16x16x32_bf16 v[72:75], v[152:155], v[204:207], v[72:75]
	s_barrier
	s_add_i32 s58, 0, 0x14000
	s_add_i32 s55, s55, s40
	ds_read_b128 v[208:211], v225
	ds_read_b128 v[212:215], v225 offset:1024
	ds_read_b128 v[216:219], v225 offset:2048
	ds_read_b128 v[220:223], v225 offset:3072
	s_add_u32 vcc_lo, s4, s0
	s_addc_u32 vcc_hi, s5, s1
	s_mov_b32 m0, s55
	s_nop 0
	global_load_lds_dwordx4 v144, s[4:5]
	s_add_i32 m0, s55, 0x2000
	s_nop 0
	global_load_lds_dwordx4 v136, s[4:5]
	s_barrier
	s_waitcnt lgkmcnt(0)
	v_mfma_f32_16x16x32_bf16 v[116:119], v[208:211], v[160:163], v[116:119]
	v_mfma_f32_16x16x32_bf16 v[112:115], v[216:219], v[160:163], v[112:115]
	v_mfma_f32_16x16x32_bf16 v[100:103], v[208:211], v[168:171], v[100:103]
	v_mfma_f32_16x16x32_bf16 v[96:99], v[216:219], v[168:171], v[96:99]
	v_mfma_f32_16x16x32_bf16 v[84:87], v[208:211], v[176:179], v[84:87]
	v_mfma_f32_16x16x32_bf16 v[80:83], v[216:219], v[176:179], v[80:83]
	v_mfma_f32_16x16x32_bf16 v[68:71], v[208:211], v[200:203], v[68:71]
	v_mfma_f32_16x16x32_bf16 v[64:67], v[216:219], v[200:203], v[64:67]
	v_mfma_f32_16x16x32_bf16 v[116:119], v[212:215], v[164:167], v[116:119]
	v_mfma_f32_16x16x32_bf16 v[112:115], v[220:223], v[164:167], v[112:115]
	v_mfma_f32_16x16x32_bf16 v[100:103], v[212:215], v[172:175], v[100:103]
	v_mfma_f32_16x16x32_bf16 v[96:99], v[220:223], v[172:175], v[96:99]
	v_mfma_f32_16x16x32_bf16 v[84:87], v[212:215], v[196:199], v[84:87]
	v_mfma_f32_16x16x32_bf16 v[80:83], v[220:223], v[196:199], v[80:83]
	v_mfma_f32_16x16x32_bf16 v[68:71], v[212:215], v[204:207], v[68:71]
	v_mfma_f32_16x16x32_bf16 v[64:67], v[220:223], v[204:207], v[64:67]
	s_mov_b32 m0, s41
	s_add_u32 s100, s28, s0
	s_addc_u32 s101, s29, s1
	s_barrier
	ds_read_b128 v[160:163], v159 offset:16384
	ds_read_b128 v[164:167], v159 offset:17408
	ds_read_b128 v[168:171], v159 offset:18432
	ds_read_b128 v[172:175], v159 offset:19456
	ds_read_b128 v[176:179], v159 offset:20480
	ds_read_b128 v[196:199], v159 offset:21504
	ds_read_b128 v[200:203], v159 offset:22528
	ds_read_b128 v[204:207], v159 offset:23552
	global_load_lds_dwordx4 v140, s[28:29]
	s_mov_b32 m0, s42
	s_nop 0
	global_load_lds_dwordx4 v138, s[28:29]
	s_barrier
	s_waitcnt lgkmcnt(0)
	v_mfma_f32_16x16x32_bf16 v[60:63], v[128:131], v[160:163], v[60:63]
	v_mfma_f32_16x16x32_bf16 v[56:59], v[148:151], v[160:163], v[56:59]
	v_mfma_f32_16x16x32_bf16 v[44:47], v[128:131], v[168:171], v[44:47]
	v_mfma_f32_16x16x32_bf16 v[40:43], v[148:151], v[168:171], v[40:43]
	v_mfma_f32_16x16x32_bf16 v[28:31], v[128:131], v[176:179], v[28:31]
	v_mfma_f32_16x16x32_bf16 v[24:27], v[148:151], v[176:179], v[24:27]
	v_mfma_f32_16x16x32_bf16 v[12:15], v[128:131], v[200:203], v[12:15]
	v_mfma_f32_16x16x32_bf16 v[8:11], v[148:151], v[200:203], v[8:11]
	v_mfma_f32_16x16x32_bf16 v[60:63], v[132:135], v[164:167], v[60:63]
	v_mfma_f32_16x16x32_bf16 v[56:59], v[152:155], v[164:167], v[56:59]
	v_mfma_f32_16x16x32_bf16 v[44:47], v[132:135], v[172:175], v[44:47]
	v_mfma_f32_16x16x32_bf16 v[40:43], v[152:155], v[172:175], v[40:43]
	v_mfma_f32_16x16x32_bf16 v[28:31], v[132:135], v[196:199], v[28:31]
	v_mfma_f32_16x16x32_bf16 v[24:27], v[152:155], v[196:199], v[24:27]
	v_mfma_f32_16x16x32_bf16 v[12:15], v[132:135], v[204:207], v[12:15]
	v_mfma_f32_16x16x32_bf16 v[8:11], v[152:155], v[204:207], v[8:11]
	s_barrier
	s_add_u32 s56, s4, 0x40000
	s_addc_u32 s57, s5, 0
	s_add_i32 s55, s58, s40
	s_mov_b32 m0, s55
	s_nop 0
	global_load_lds_dwordx4 v144, s[56:57]
	s_add_i32 m0, s55, 0x2000
	s_nop 0
	global_load_lds_dwordx4 v136, s[56:57]
	s_waitcnt vmcnt(6)
	s_barrier
; #define PG8_STAGE(bufoff, gbase, voff) do { _Pragma("unroll") for (int _i = 0; _i < 2; ++_i) \
;     __builtin_amdgcn_global_load_lds((const unsigned*)((const char*)(gbase) + (voff)[_i]), (LAS unsigned*)(lds + (bufoff) + ldsw + _i * 8192), 16, 0, 0); } while (0)
; #define PG8_LDA(dst, b, h) do { _Pragma("unroll") for (int m = 0; m < 4; ++m) _Pragma("unroll") for (int k = 0; k < 2; ++k) dst[m][k] = *(const LAS bf16x8*)(lds + PG8_SA(b, h) + aoff + m * 2048 + k * 1024); } while (0)
; #define PG8_LDB(dst, b, h) do { _Pragma("unroll") for (int n = 0; n < 2; ++n) _Pragma("unroll") for (int k = 0; k < 2; ++k) dst[n][k] = *(const LAS bf16x8*)(lds + PG8_SB(b, h) + boff + n * 2048 + k * 1024); } while (0)
; #define PG8_MMA(ai, bj, At, Bt) do { __builtin_amdgcn_s_setprio(1); _Pragma("unroll") for (int m = 0; m < 4; ++m) _Pragma("unroll") for (int n = 0; n < 2; ++n) _Pragma("unroll") for (int k = 0; k < 2; ++k) \
;     acc[ai][bj][m][n] = __builtin_amdgcn_mfma_f32_16x16x32_bf16(Bt[n][k], At[m][k], acc[ai][bj][m][n], 0, 0, 0); __builtin_amdgcn_s_setprio(0); } while (0)
; #define PG8_WAIT_L(n) asm volatile("s_waitcnt lgkmcnt(" #n ")" ::: "memory")
; #define PG8_BAR __builtin_amdgcn_s_barrier()
; #define PG8_SCHED __builtin_amdgcn_sched_barrier(0)
; template <class Epi, class Sched>
; DI void gemm_phase(LAS unsigned char* lds, const Gemm g, const Sched& S, const Epi& E) {
;     ...
;       PG8_LDB(B0, 1, 0); PG8_SCHED; PG8_LDA(At, 1, 0); PG8_STAGE(PG8_SA(0, 1), a2 + hstep, voffA);
;       PG8_WAIT_L(8); PG8_BAR; PG8_WAIT_L(0); PG8_MMA(0, 0, At, B0); PG8_BAR; PG8_SCHED;
;       PG8_LDB(B1, 1, 1); PG8_STAGE(PG8_SB(1, 0), b3, voffB);
;       PG8_BAR; PG8_WAIT_L(0); PG8_MMA(0, 1, At, B1); PG8_BAR;
;       PG8_LDA(At, 1, 1); PG8_STAGE(PG8_SA(1, 0), a3, voffA);
;       PG8_BAR; PG8_WAIT_L(0); PG8_MMA(1, 0, At, B0); PG8_BAR; PG8_SCHED;
	v_mfma_f32_16x16x32_bf16 v[52:55], v[208:211], v[160:163], v[52:55]
	v_mfma_f32_16x16x32_bf16 v[48:51], v[216:219], v[160:163], v[48:51]
	v_mfma_f32_16x16x32_bf16 v[36:39], v[208:211], v[168:171], v[36:39]
	v_mfma_f32_16x16x32_bf16 v[32:35], v[216:219], v[168:171], v[32:35]
	v_mfma_f32_16x16x32_bf16 v[20:23], v[208:211], v[176:179], v[20:23]
	v_mfma_f32_16x16x32_bf16 v[16:19], v[216:219], v[176:179], v[16:19]
	v_mfma_f32_16x16x32_bf16 v[4:7], v[208:211], v[200:203], v[4:7]
	v_mfma_f32_16x16x32_bf16 v[0:3], v[216:219], v[200:203], v[0:3]
	v_mfma_f32_16x16x32_bf16 v[52:55], v[212:215], v[164:167], v[52:55]
	v_mfma_f32_16x16x32_bf16 v[48:51], v[220:223], v[164:167], v[48:51]
	v_mfma_f32_16x16x32_bf16 v[36:39], v[212:215], v[172:175], v[36:39]
	v_mfma_f32_16x16x32_bf16 v[32:35], v[220:223], v[172:175], v[32:35]
	v_mfma_f32_16x16x32_bf16 v[20:23], v[212:215], v[196:199], v[20:23]
	v_mfma_f32_16x16x32_bf16 v[16:19], v[220:223], v[196:199], v[16:19]
	v_mfma_f32_16x16x32_bf16 v[4:7], v[212:215], v[204:207], v[4:7]
	v_mfma_f32_16x16x32_bf16 v[0:3], v[220:223], v[204:207], v[0:3]
	s_add_i32 s55, 0, 0x18000
	s_barrier
	ds_read_b128 v[128:131], v226
	ds_read_b128 v[132:135], v226 offset:1024
	ds_read_b128 v[148:151], v226 offset:2048
	ds_read_b128 v[152:155], v226 offset:3072
	s_add_u32 s28, s28, 0x40000
	s_addc_u32 s29, s29, 0
	s_mov_b32 m0, s43
	ds_read_b128 v[160:163], v159 offset:32768
	ds_read_b128 v[164:167], v159 offset:33792
	ds_read_b128 v[168:171], v159 offset:34816
	ds_read_b128 v[172:175], v159 offset:35840
	ds_read_b128 v[176:179], v159 offset:36864
	ds_read_b128 v[196:199], v159 offset:37888
	ds_read_b128 v[200:203], v159 offset:38912
	ds_read_b128 v[204:207], v159 offset:39936
	global_load_lds_dwordx4 v140, s[28:29]
	s_mov_b32 m0, s44
	s_nop 0
	global_load_lds_dwordx4 v138, s[28:29]
	s_waitcnt lgkmcnt(8)
	s_barrier
	s_waitcnt lgkmcnt(0)
	v_mfma_f32_16x16x32_bf16 v[124:127], v[128:131], v[160:163], v[124:127]
	v_mfma_f32_16x16x32_bf16 v[120:123], v[148:151], v[160:163], v[120:123]
	v_mfma_f32_16x16x32_bf16 v[108:111], v[128:131], v[168:171], v[108:111]
	v_mfma_f32_16x16x32_bf16 v[104:107], v[148:151], v[168:171], v[104:107]
	v_mfma_f32_16x16x32_bf16 v[92:95], v[128:131], v[176:179], v[92:95]
	v_mfma_f32_16x16x32_bf16 v[88:91], v[148:151], v[176:179], v[88:91]
	v_mfma_f32_16x16x32_bf16 v[76:79], v[128:131], v[200:203], v[76:79]
	v_mfma_f32_16x16x32_bf16 v[72:75], v[148:151], v[200:203], v[72:75]
	v_mfma_f32_16x16x32_bf16 v[124:127], v[132:135], v[164:167], v[124:127]
	v_mfma_f32_16x16x32_bf16 v[120:123], v[152:155], v[164:167], v[120:123]
	v_mfma_f32_16x16x32_bf16 v[108:111], v[132:135], v[172:175], v[108:111]
	v_mfma_f32_16x16x32_bf16 v[104:107], v[152:155], v[172:175], v[104:107]
	v_mfma_f32_16x16x32_bf16 v[92:95], v[132:135], v[196:199], v[92:95]
	v_mfma_f32_16x16x32_bf16 v[88:91], v[152:155], v[196:199], v[88:91]
	v_mfma_f32_16x16x32_bf16 v[76:79], v[132:135], v[204:207], v[76:79]
	v_mfma_f32_16x16x32_bf16 v[72:75], v[152:155], v[204:207], v[72:75]
	s_barrier
	s_add_i32 s28, 0, 0x1c000
	s_add_i32 s29, s55, s40
	s_mov_b32 m0, s29
	ds_read_b128 v[208:211], v227
	ds_read_b128 v[212:215], v227 offset:1024
	ds_read_b128 v[216:219], v227 offset:2048
	ds_read_b128 v[220:223], v227 offset:3072
	global_load_lds_dwordx4 v144, vcc
	s_add_i32 m0, s29, 0x2000
	s_nop 0
	global_load_lds_dwordx4 v136, vcc
	s_barrier
	s_waitcnt lgkmcnt(0)
	v_mfma_f32_16x16x32_bf16 v[116:119], v[208:211], v[160:163], v[116:119]
	v_mfma_f32_16x16x32_bf16 v[112:115], v[216:219], v[160:163], v[112:115]
	v_mfma_f32_16x16x32_bf16 v[100:103], v[208:211], v[168:171], v[100:103]
	v_mfma_f32_16x16x32_bf16 v[96:99], v[216:219], v[168:171], v[96:99]
	v_mfma_f32_16x16x32_bf16 v[84:87], v[208:211], v[176:179], v[84:87]
	v_mfma_f32_16x16x32_bf16 v[80:83], v[216:219], v[176:179], v[80:83]
	v_mfma_f32_16x16x32_bf16 v[68:71], v[208:211], v[200:203], v[68:71]
	v_mfma_f32_16x16x32_bf16 v[64:67], v[216:219], v[200:203], v[64:67]
	v_mfma_f32_16x16x32_bf16 v[116:119], v[212:215], v[164:167], v[116:119]
	v_mfma_f32_16x16x32_bf16 v[112:115], v[220:223], v[164:167], v[112:115]
	v_mfma_f32_16x16x32_bf16 v[100:103], v[212:215], v[172:175], v[100:103]
	v_mfma_f32_16x16x32_bf16 v[96:99], v[220:223], v[172:175], v[96:99]
	v_mfma_f32_16x16x32_bf16 v[84:87], v[212:215], v[196:199], v[84:87]
	v_mfma_f32_16x16x32_bf16 v[80:83], v[220:223], v[196:199], v[80:83]
	v_mfma_f32_16x16x32_bf16 v[68:71], v[212:215], v[204:207], v[68:71]
	v_mfma_f32_16x16x32_bf16 v[64:67], v[220:223], v[204:207], v[64:67]
	s_mov_b32 m0, s49
	s_barrier
	ds_read_b128 v[160:163], v159 offset:49152
	ds_read_b128 v[164:167], v159 offset:50176
	ds_read_b128 v[168:171], v159 offset:51200
	ds_read_b128 v[172:175], v159 offset:52224
	ds_read_b128 v[176:179], v159 offset:53248
	ds_read_b128 v[196:199], v159 offset:54272
	ds_read_b128 v[200:203], v159 offset:55296
	ds_read_b128 v[204:207], v159 offset:56320
	global_load_lds_dwordx4 v140, s[100:101]
	s_mov_b32 m0, s50
	s_nop 0
	global_load_lds_dwordx4 v138, s[100:101]
	s_barrier
	s_waitcnt lgkmcnt(0)
	v_mfma_f32_16x16x32_bf16 v[60:63], v[128:131], v[160:163], v[60:63]
	v_mfma_f32_16x16x32_bf16 v[56:59], v[148:151], v[160:163], v[56:59]
	v_mfma_f32_16x16x32_bf16 v[44:47], v[128:131], v[168:171], v[44:47]
	v_mfma_f32_16x16x32_bf16 v[40:43], v[148:151], v[168:171], v[40:43]
	v_mfma_f32_16x16x32_bf16 v[28:31], v[128:131], v[176:179], v[28:31]
	v_mfma_f32_16x16x32_bf16 v[24:27], v[148:151], v[176:179], v[24:27]
	v_mfma_f32_16x16x32_bf16 v[12:15], v[128:131], v[200:203], v[12:15]
	v_mfma_f32_16x16x32_bf16 v[8:11], v[148:151], v[200:203], v[8:11]
	v_mfma_f32_16x16x32_bf16 v[60:63], v[132:135], v[164:167], v[60:63]
	v_mfma_f32_16x16x32_bf16 v[56:59], v[152:155], v[164:167], v[56:59]
	v_mfma_f32_16x16x32_bf16 v[44:47], v[132:135], v[172:175], v[44:47]
	v_mfma_f32_16x16x32_bf16 v[40:43], v[152:155], v[172:175], v[40:43]
	v_mfma_f32_16x16x32_bf16 v[28:31], v[132:135], v[196:199], v[28:31]
	v_mfma_f32_16x16x32_bf16 v[24:27], v[152:155], v[196:199], v[24:27]
	v_mfma_f32_16x16x32_bf16 v[12:15], v[132:135], v[204:207], v[12:15]
	v_mfma_f32_16x16x32_bf16 v[8:11], v[152:155], v[204:207], v[8:11]
	s_barrier
; DI float bf2f(unsigned v) { return __uint_as_float(v << 16); }
; #define PG8_STAGE(bufoff, gbase, voff) do { _Pragma("unroll") for (int _i = 0; _i < 2; ++_i) \
;     __builtin_amdgcn_global_load_lds((const unsigned*)((const char*)(gbase) + (voff)[_i]), (LAS unsigned*)(lds + (bufoff) + ldsw + _i * 8192), 16, 0, 0); } while (0)
; #define PG8_MMA(ai, bj, At, Bt) do { __builtin_amdgcn_s_setprio(1); _Pragma("unroll") for (int m = 0; m < 4; ++m) _Pragma("unroll") for (int n = 0; n < 2; ++n) _Pragma("unroll") for (int k = 0; k < 2; ++k) \
;     acc[ai][bj][m][n] = __builtin_amdgcn_mfma_f32_16x16x32_bf16(Bt[n][k], At[m][k], acc[ai][bj][m][n], 0, 0, 0); __builtin_amdgcn_s_setprio(0); } while (0)
; #define PG8_WAIT_V(n) asm volatile("s_waitcnt vmcnt(" #n ")" ::: "memory")
; #define PG8_BAR __builtin_amdgcn_s_barrier()
; template <class Epi, class Sched>
; DI void gemm_phase(LAS unsigned char* lds, const Gemm g, const Sched& S, const Epi& E) {
;     ...
;       PG8_STAGE(PG8_SB(1, 1), b3 + hstep, voffB);
;       PG8_WAIT_V(6); PG8_BAR; PG8_MMA(1, 1, At, B1); PG8_BAR;
;   DI void operator()(const f32x4 (&acc)[2][2][4][2], const pg8::Unit& u, int wr, int wc, int fr_, int fq_) const {
;     ...
;             } else if (EPI == EPI_RESID) {
;               if (n == 0) {
;                 const int f8 = u.pn * 256 + bj * 128 + wc * 32 + 8 * fq;
;                 const f32x4 v1 = acc[ai][bj][m][1];
;                 f32x4 r0, r1;
;                 if (rsrc) {
;                   r0 = *(const f32x4*)(rsrc + (size_t)token * 1024 + f8); r1 = *(const f32x4*)(rsrc + (size_t)token * 1024 + f8 + 4);
;                 } else {
;                   const u32x4 xu = *(const u32x4*)(xr + (size_t)token * 1024 + f8);
;                   r0 = (f32x4){bf2f(xu.x & 0xffffu), bf2f(xu.x >> 16), bf2f(xu.y & 0xffffu), bf2f(xu.y >> 16)};
;                   r1 = (f32x4){bf2f(xu.z & 0xffffu), bf2f(xu.z >> 16), bf2f(xu.w & 0xffffu), bf2f(xu.w >> 16)};
;                 }
;                 r0 += v; r1 += v1;
	s_add_u32 s4, s4, 0x40080
	s_addc_u32 s5, s5, 0
	s_add_i32 s28, s28, s40
	s_mov_b32 m0, s28
	s_nop 0
	global_load_lds_dwordx4 v144, s[4:5]
	s_add_i32 m0, s28, 0x2000
	s_nop 0
	global_load_lds_dwordx4 v136, s[4:5]
	s_waitcnt vmcnt(6)
	s_barrier
	v_mfma_f32_16x16x32_bf16 v[52:55], v[208:211], v[160:163], v[52:55]
	v_mfma_f32_16x16x32_bf16 v[48:51], v[216:219], v[160:163], v[48:51]
	v_mfma_f32_16x16x32_bf16 v[36:39], v[208:211], v[168:171], v[36:39]
	v_mfma_f32_16x16x32_bf16 v[32:35], v[216:219], v[168:171], v[32:35]
	v_mfma_f32_16x16x32_bf16 v[20:23], v[208:211], v[176:179], v[20:23]
	v_mfma_f32_16x16x32_bf16 v[16:19], v[216:219], v[176:179], v[16:19]
	v_mfma_f32_16x16x32_bf16 v[4:7], v[208:211], v[200:203], v[4:7]
	v_mfma_f32_16x16x32_bf16 v[0:3], v[216:219], v[200:203], v[0:3]
	v_mfma_f32_16x16x32_bf16 v[52:55], v[212:215], v[164:167], v[52:55]
	v_mfma_f32_16x16x32_bf16 v[48:51], v[220:223], v[164:167], v[48:51]
	v_mfma_f32_16x16x32_bf16 v[36:39], v[212:215], v[172:175], v[36:39]
	v_mfma_f32_16x16x32_bf16 v[32:35], v[220:223], v[172:175], v[32:35]
	v_mfma_f32_16x16x32_bf16 v[20:23], v[212:215], v[196:199], v[20:23]
	v_mfma_f32_16x16x32_bf16 v[16:19], v[220:223], v[196:199], v[16:19]
	v_mfma_f32_16x16x32_bf16 v[4:7], v[212:215], v[204:207], v[4:7]
	v_mfma_f32_16x16x32_bf16 v[0:3], v[220:223], v[204:207], v[0:3]
	s_add_i32 s54, s54, 2
	s_add_u32 s2, s2, 0x100
	s_addc_u32 s3, s3, 0
	s_add_u32 s52, s52, 0x100
	s_addc_u32 s53, s53, 0
	s_cmp_gt_u32 s54, 13
	s_barrier
	s_cbranch_scc0 .LBB0_1644
	s_lshl_b32 s2, s34, 8
	v_mov_b32_e32 v161, v182
	s_add_i32 s2, s2, s47
	v_cndmask_b32_e64 v130, 0, 1, s[14:15]
	v_and_or_b32 v150, v161, 15, s2
	s_lshl_b32 s2, s24, 8
	v_bfe_u32 v160, v161, 4, 2
	s_or_b32 s2, s2, s48
	v_ashrrev_i32_e32 v151, 31, v150
	v_lshl_or_b32 v148, v160, 3, s2
	v_lshlrev_b64 v[128:129], 12, v[150:151]
	v_ashrrev_i32_e32 v149, 31, v148
	v_lshl_add_u64 v[128:129], s[6:7], 0, v[128:129]
	v_cmp_ne_u32_e64 s[2:3], 1, v130
	s_andn2_b64 vcc, exec, s[14:15]
	v_lshl_add_u64 v[154:155], v[148:149], 2, v[128:129]
	s_cbranch_vccnz .LBB0_1647
	v_lshlrev_b32_e32 v251, 2, v148
	v_lshl_add_u32 v251, v150, 12, v251
	global_load_dwordx4 v[162:165], v251, s[6:7]
	global_load_dwordx4 v[166:169], v251, s[6:7] offset:16
	global_load_dwordx4 v[170:173], v251, s[6:7] offset:512
	global_load_dwordx4 v[174:177], v251, s[6:7] offset:528
	v_add_u32_e32 v251, 0x10000, v251
	global_load_dwordx4 v[178:181], v251, s[6:7]
	global_load_dwordx4 v[196:199], v251, s[6:7] offset:16
	global_load_dwordx4 v[200:203], v251, s[6:7] offset:512
	global_load_dwordx4 v[204:207], v251, s[6:7] offset:528
	v_add_u32_e32 v251, 0x10000, v251
	global_load_dwordx4 v[208:211], v251, s[6:7]
	global_load_dwordx4 v[212:215], v251, s[6:7] offset:16
	global_load_dwordx4 v[216:219], v251, s[6:7] offset:512
	global_load_dwordx4 v[220:223], v251, s[6:7] offset:528
	v_add_u32_e32 v251, 0x10000, v251
	global_load_dwordx4 v[224:227], v251, s[6:7]
	global_load_dwordx4 v[228:231], v251, s[6:7] offset:16
	global_load_dwordx4 v[232:235], v251, s[6:7] offset:512
	global_load_dwordx4 v[242:245], v251, s[6:7] offset:528
	s_waitcnt vmcnt(0)
	v_mov_b64_e32 v[132:133], v[166:167]
	v_mov_b64_e32 v[134:135], v[168:169]
	v_mov_b64_e32 v[128:129], v[162:163]
	v_mov_b64_e32 v[130:131], v[164:165]
	s_mov_b64 s[4:5], 0
	s_branch .LBB0_1648
.Lrw_1644_0:
	s_branch .LBB0_1650
.Lrw_1644_1:
	s_branch .LBB0_1653
.Lrw_1644_2:
	s_branch .LBB0_1661
.Lrw_1644_3:
	s_branch .LBB0_1664
.Lrw_1644_4:
	s_branch .LBB0_1672
.Lrw_1644_5:
	s_branch .LBB0_1675
.Lrw_1644_6:
	s_branch .LBB0_1683
.Lrw_1644_7:
	s_branch .LBB0_1686
.Lrw_1644_8:
	s_branch .LBB0_1694
.Lrw_1644_9:
	s_branch .LBB0_1697
.Lrw_1644_10:
	s_branch .LBB0_1705
.Lrw_1644_11:
	s_branch .LBB0_1708
.Lrw_1644_12:
	s_branch .LBB0_1716
.Lrw_1644_13:
	s_branch .LBB0_1719
.Lrw_1644_14:
	s_branch .LBB0_1727
.Lrw_1644_15:
	s_branch .LBB0_1730
.LBB0_1647:
	s_mov_b64 s[4:5], -1
	v_lshlrev_b32_e32 v250, 1, v148
	v_lshl_add_u32 v250, v150, 11, v250
	global_load_dwordx4 v[162:165], v250, s[12:13]
	global_load_dwordx4 v[166:169], v250, s[12:13] offset:256
	v_add_u32_e32 v250, 0x8000, v250
	global_load_dwordx4 v[170:173], v250, s[12:13]
	global_load_dwordx4 v[174:177], v250, s[12:13] offset:256
	v_add_u32_e32 v250, 0x8000, v250
	global_load_dwordx4 v[178:181], v250, s[12:13]
	global_load_dwordx4 v[196:199], v250, s[12:13] offset:256
	v_add_u32_e32 v250, 0x8000, v250
	global_load_dwordx4 v[200:203], v250, s[12:13]
	global_load_dwordx4 v[204:207], v250, s[12:13] offset:256
	v_add_u32_e32 v250, 0x28000, v250
	global_load_dwordx4 v[208:211], v250, s[12:13]
	global_load_dwordx4 v[212:215], v250, s[12:13] offset:256
	v_add_u32_e32 v250, 0x8000, v250
	global_load_dwordx4 v[216:219], v250, s[12:13]
	global_load_dwordx4 v[220:223], v250, s[12:13] offset:256
	v_add_u32_e32 v250, 0x8000, v250
	global_load_dwordx4 v[224:227], v250, s[12:13]
	global_load_dwordx4 v[228:231], v250, s[12:13] offset:256
	v_add_u32_e32 v250, 0x8000, v250
	global_load_dwordx4 v[232:235], v250, s[12:13]
	global_load_dwordx4 v[242:245], v250, s[12:13] offset:256

; DI float bf2f(unsigned v) { return __uint_as_float(v << 16); }
;   DI void operator()(const f32x4 (&acc)[2][2][4][2], const pg8::Unit& u, int wr, int wc, int fr_, int fq_) const {
;     ...
;             } else if (EPI == EPI_RESID) {
;               if (n == 0) {
;                 const int f8 = u.pn * 256 + bj * 128 + wc * 32 + 8 * fq;
;                 const f32x4 v1 = acc[ai][bj][m][1];
;                 f32x4 r0, r1;
;                 if (rsrc) {
;                   r0 = *(const f32x4*)(rsrc + (size_t)token * 1024 + f8); r1 = *(const f32x4*)(rsrc + (size_t)token * 1024 + f8 + 4);
;                 } else {
;                   const u32x4 xu = *(const u32x4*)(xr + (size_t)token * 1024 + f8);
;                   r0 = (f32x4){bf2f(xu.x & 0xffffu), bf2f(xu.x >> 16), bf2f(xu.y & 0xffffu), bf2f(xu.y >> 16)};
;                   r1 = (f32x4){bf2f(xu.z & 0xffffu), bf2f(xu.z >> 16), bf2f(xu.w & 0xffffu), bf2f(xu.w >> 16)};
;                 }
;                 r0 += v; r1 += v1;
;                 st_bf8(xr + (size_t)token * 1024 + f8, r0, r1, 1.f);
.LBB0_1650:
	v_pk_add_f32 v[130:131], v[126:127], v[130:131]
	v_pk_add_f32 v[156:157], v[124:125], v[128:129]
	v_pk_add_f32 v[128:129], v[122:123], v[134:135]
	v_pk_add_f32 v[132:133], v[120:121], v[132:133]
	v_cvt_pk_bf16_f32 v120, v156, v157
	v_cvt_pk_bf16_f32 v121, v130, v131
	v_cvt_pk_bf16_f32 v122, v132, v133
	v_cvt_pk_bf16_f32 v123, v128, v129
	s_and_b64 vcc, exec, s[2:3]
	global_store_dwordx4 v[152:153], v[120:123], off
	s_cbranch_vccnz .LBB0_1657
	v_mov_b64_e32 v[124:125], v[174:175]
	v_mov_b64_e32 v[126:127], v[176:177]
	v_mov_b64_e32 v[120:121], v[170:171]
	v_mov_b64_e32 v[122:123], v[172:173]
	s_cbranch_execnz .Lrw_1644_1

; DI float bf2f(unsigned v) { return __uint_as_float(v << 16); }
;   DI void operator()(const f32x4 (&acc)[2][2][4][2], const pg8::Unit& u, int wr, int wc, int fr_, int fq_) const {
;     ...
;             } else if (EPI == EPI_RESID) {
;               if (n == 0) {
;                 const int f8 = u.pn * 256 + bj * 128 + wc * 32 + 8 * fq;
;                 const f32x4 v1 = acc[ai][bj][m][1];
;                 f32x4 r0, r1;
;                 if (rsrc) {
;                   r0 = *(const f32x4*)(rsrc + (size_t)token * 1024 + f8); r1 = *(const f32x4*)(rsrc + (size_t)token * 1024 + f8 + 4);
;                 } else {
;                   const u32x4 xu = *(const u32x4*)(xr + (size_t)token * 1024 + f8);
;                   r0 = (f32x4){bf2f(xu.x & 0xffffu), bf2f(xu.x >> 16), bf2f(xu.y & 0xffffu), bf2f(xu.y >> 16)};
;                   r1 = (f32x4){bf2f(xu.z & 0xffffu), bf2f(xu.z >> 16), bf2f(xu.w & 0xffffu), bf2f(xu.w >> 16)};
;                 }
;                 r0 += v; r1 += v1;
.LBB0_1655:
	s_or_b64 exec, exec, s[34:35]
	v_or_b32_e32 v120, 16, v150
	v_ashrrev_i32_e32 v121, 31, v120
	s_waitcnt lgkmcnt(0)
	v_lshlrev_b64 v[112:113], 12, v[120:121]
	v_lshl_add_u64 v[112:113], s[6:7], 0, v[112:113]
	s_and_b64 vcc, exec, s[2:3]
	v_lshl_add_u64 v[124:125], v[148:149], 2, v[112:113]
	s_cbranch_vccnz .LBB0_1658
	v_mov_b64_e32 v[116:117], v[196:197]
	v_mov_b64_e32 v[118:119], v[198:199]
	v_mov_b64_e32 v[112:113], v[178:179]
	v_mov_b64_e32 v[114:115], v[180:181]
	s_mov_b64 s[34:35], 0
	s_branch .LBB0_1659

; DI float bf2f(unsigned v) { return __uint_as_float(v << 16); }
;   DI void operator()(const f32x4 (&acc)[2][2][4][2], const pg8::Unit& u, int wr, int wc, int fr_, int fq_) const {
;     ...
;             } else if (EPI == EPI_RESID) {
;               if (n == 0) {
;                 const int f8 = u.pn * 256 + bj * 128 + wc * 32 + 8 * fq;
;                 const f32x4 v1 = acc[ai][bj][m][1];
;                 f32x4 r0, r1;
;                 if (rsrc) {
;                   r0 = *(const f32x4*)(rsrc + (size_t)token * 1024 + f8); r1 = *(const f32x4*)(rsrc + (size_t)token * 1024 + f8 + 4);
;                 } else {
;                   const u32x4 xu = *(const u32x4*)(xr + (size_t)token * 1024 + f8);
;                   r0 = (f32x4){bf2f(xu.x & 0xffffu), bf2f(xu.x >> 16), bf2f(xu.y & 0xffffu), bf2f(xu.y >> 16)};
;                   r1 = (f32x4){bf2f(xu.z & 0xffffu), bf2f(xu.z >> 16), bf2f(xu.w & 0xffffu), bf2f(xu.w >> 16)};
;                 }
;                 r0 += v; r1 += v1;
;                 st_bf8(xr + (size_t)token * 1024 + f8, r0, r1, 1.f);
.LBB0_1661:
	v_pk_add_f32 v[114:115], v[110:111], v[114:115]
	v_pk_add_f32 v[126:127], v[108:109], v[112:113]
	v_pk_add_f32 v[112:113], v[106:107], v[118:119]
	v_pk_add_f32 v[116:117], v[104:105], v[116:117]
	v_cvt_pk_bf16_f32 v104, v126, v127
	v_cvt_pk_bf16_f32 v105, v114, v115
	v_cvt_pk_bf16_f32 v106, v116, v117
	v_cvt_pk_bf16_f32 v107, v112, v113
	s_and_b64 vcc, exec, s[2:3]
	global_store_dwordx4 v[122:123], v[104:107], off
	s_cbranch_vccnz .LBB0_1668
	v_mov_b64_e32 v[108:109], v[204:205]
	v_mov_b64_e32 v[110:111], v[206:207]
	v_mov_b64_e32 v[104:105], v[200:201]
	v_mov_b64_e32 v[106:107], v[202:203]
	s_cbranch_execnz .Lrw_1644_3

; DI float bf2f(unsigned v) { return __uint_as_float(v << 16); }
;   DI void operator()(const f32x4 (&acc)[2][2][4][2], const pg8::Unit& u, int wr, int wc, int fr_, int fq_) const {
;     ...
;             } else if (EPI == EPI_RESID) {
;               if (n == 0) {
;                 const int f8 = u.pn * 256 + bj * 128 + wc * 32 + 8 * fq;
;                 const f32x4 v1 = acc[ai][bj][m][1];
;                 f32x4 r0, r1;
;                 if (rsrc) {
;                   r0 = *(const f32x4*)(rsrc + (size_t)token * 1024 + f8); r1 = *(const f32x4*)(rsrc + (size_t)token * 1024 + f8 + 4);
;                 } else {
;                   const u32x4 xu = *(const u32x4*)(xr + (size_t)token * 1024 + f8);
;                   r0 = (f32x4){bf2f(xu.x & 0xffffu), bf2f(xu.x >> 16), bf2f(xu.y & 0xffffu), bf2f(xu.y >> 16)};
;                   r1 = (f32x4){bf2f(xu.z & 0xffffu), bf2f(xu.z >> 16), bf2f(xu.w & 0xffffu), bf2f(xu.w >> 16)};
;                 }
;                 r0 += v; r1 += v1;
.LBB0_1666:
	s_or_b64 exec, exec, s[34:35]
	v_or_b32_e32 v104, 32, v150
	v_ashrrev_i32_e32 v105, 31, v104
	s_waitcnt lgkmcnt(0)
	v_lshlrev_b64 v[96:97], 12, v[104:105]
	v_lshl_add_u64 v[96:97], s[6:7], 0, v[96:97]
	s_and_b64 vcc, exec, s[2:3]
	v_lshl_add_u64 v[108:109], v[148:149], 2, v[96:97]
	s_cbranch_vccnz .LBB0_1669
	v_mov_b64_e32 v[100:101], v[212:213]
	v_mov_b64_e32 v[102:103], v[214:215]
	v_mov_b64_e32 v[96:97], v[208:209]
	v_mov_b64_e32 v[98:99], v[210:211]
	s_mov_b64 s[34:35], 0
	s_branch .LBB0_1670

; DI float bf2f(unsigned v) { return __uint_as_float(v << 16); }
;   DI void operator()(const f32x4 (&acc)[2][2][4][2], const pg8::Unit& u, int wr, int wc, int fr_, int fq_) const {
;     ...
;             } else if (EPI == EPI_RESID) {
;               if (n == 0) {
;                 const int f8 = u.pn * 256 + bj * 128 + wc * 32 + 8 * fq;
;                 const f32x4 v1 = acc[ai][bj][m][1];
;                 f32x4 r0, r1;
;                 if (rsrc) {
;                   r0 = *(const f32x4*)(rsrc + (size_t)token * 1024 + f8); r1 = *(const f32x4*)(rsrc + (size_t)token * 1024 + f8 + 4);
;                 } else {
;                   const u32x4 xu = *(const u32x4*)(xr + (size_t)token * 1024 + f8);
;                   r0 = (f32x4){bf2f(xu.x & 0xffffu), bf2f(xu.x >> 16), bf2f(xu.y & 0xffffu), bf2f(xu.y >> 16)};
;                   r1 = (f32x4){bf2f(xu.z & 0xffffu), bf2f(xu.z >> 16), bf2f(xu.w & 0xffffu), bf2f(xu.w >> 16)};
;                 }
;                 r0 += v; r1 += v1;
;                 st_bf8(xr + (size_t)token * 1024 + f8, r0, r1, 1.f);
.LBB0_1672:
	v_pk_add_f32 v[98:99], v[94:95], v[98:99]
	v_pk_add_f32 v[110:111], v[92:93], v[96:97]
	v_pk_add_f32 v[96:97], v[90:91], v[102:103]
	v_pk_add_f32 v[100:101], v[88:89], v[100:101]
	v_cvt_pk_bf16_f32 v88, v110, v111
	v_cvt_pk_bf16_f32 v89, v98, v99
	v_cvt_pk_bf16_f32 v90, v100, v101
	v_cvt_pk_bf16_f32 v91, v96, v97
	s_and_b64 vcc, exec, s[2:3]
	global_store_dwordx4 v[106:107], v[88:91], off
	s_cbranch_vccnz .LBB0_1679
	v_mov_b64_e32 v[92:93], v[220:221]
	v_mov_b64_e32 v[94:95], v[222:223]
	v_mov_b64_e32 v[88:89], v[216:217]
	v_mov_b64_e32 v[90:91], v[218:219]
	s_cbranch_execnz .Lrw_1644_5

; DI float bf2f(unsigned v) { return __uint_as_float(v << 16); }
;   DI void operator()(const f32x4 (&acc)[2][2][4][2], const pg8::Unit& u, int wr, int wc, int fr_, int fq_) const {
;     ...
;             } else if (EPI == EPI_RESID) {
;               if (n == 0) {
;                 const int f8 = u.pn * 256 + bj * 128 + wc * 32 + 8 * fq;
;                 const f32x4 v1 = acc[ai][bj][m][1];
;                 f32x4 r0, r1;
;                 if (rsrc) {
;                   r0 = *(const f32x4*)(rsrc + (size_t)token * 1024 + f8); r1 = *(const f32x4*)(rsrc + (size_t)token * 1024 + f8 + 4);
;                 } else {
;                   const u32x4 xu = *(const u32x4*)(xr + (size_t)token * 1024 + f8);
;                   r0 = (f32x4){bf2f(xu.x & 0xffffu), bf2f(xu.x >> 16), bf2f(xu.y & 0xffffu), bf2f(xu.y >> 16)};
;                   r1 = (f32x4){bf2f(xu.z & 0xffffu), bf2f(xu.z >> 16), bf2f(xu.w & 0xffffu), bf2f(xu.w >> 16)};
;                 }
;                 r0 += v; r1 += v1;
.LBB0_1677:
	s_or_b64 exec, exec, s[34:35]
	v_or_b32_e32 v88, 48, v150
	v_ashrrev_i32_e32 v89, 31, v88
	s_waitcnt lgkmcnt(0)
	v_lshlrev_b64 v[80:81], 12, v[88:89]
	v_lshl_add_u64 v[80:81], s[6:7], 0, v[80:81]
	s_and_b64 vcc, exec, s[2:3]
	v_lshl_add_u64 v[92:93], v[148:149], 2, v[80:81]
	s_cbranch_vccnz .LBB0_1680
	v_mov_b64_e32 v[84:85], v[228:229]
	v_mov_b64_e32 v[86:87], v[230:231]
	v_mov_b64_e32 v[80:81], v[224:225]
	v_mov_b64_e32 v[82:83], v[226:227]
	s_mov_b64 s[34:35], 0
	s_branch .LBB0_1681

; DI float bf2f(unsigned v) { return __uint_as_float(v << 16); }
;   DI void operator()(const f32x4 (&acc)[2][2][4][2], const pg8::Unit& u, int wr, int wc, int fr_, int fq_) const {
;     ...
;             } else if (EPI == EPI_RESID) {
;               if (n == 0) {
;                 const int f8 = u.pn * 256 + bj * 128 + wc * 32 + 8 * fq;
;                 const f32x4 v1 = acc[ai][bj][m][1];
;                 f32x4 r0, r1;
;                 if (rsrc) {
;                   r0 = *(const f32x4*)(rsrc + (size_t)token * 1024 + f8); r1 = *(const f32x4*)(rsrc + (size_t)token * 1024 + f8 + 4);
;                 } else {
;                   const u32x4 xu = *(const u32x4*)(xr + (size_t)token * 1024 + f8);
;                   r0 = (f32x4){bf2f(xu.x & 0xffffu), bf2f(xu.x >> 16), bf2f(xu.y & 0xffffu), bf2f(xu.y >> 16)};
;                   r1 = (f32x4){bf2f(xu.z & 0xffffu), bf2f(xu.z >> 16), bf2f(xu.w & 0xffffu), bf2f(xu.w >> 16)};
;                 }
;                 r0 += v; r1 += v1;
;                 st_bf8(xr + (size_t)token * 1024 + f8, r0, r1, 1.f);
.LBB0_1683:
	v_pk_add_f32 v[82:83], v[78:79], v[82:83]
	v_pk_add_f32 v[94:95], v[76:77], v[80:81]
	v_pk_add_f32 v[80:81], v[74:75], v[86:87]
	v_pk_add_f32 v[84:85], v[72:73], v[84:85]
	v_cvt_pk_bf16_f32 v72, v94, v95
	v_cvt_pk_bf16_f32 v73, v82, v83
	v_cvt_pk_bf16_f32 v74, v84, v85
	v_cvt_pk_bf16_f32 v75, v80, v81
	s_and_b64 vcc, exec, s[2:3]
	global_store_dwordx4 v[90:91], v[72:75], off
	s_cbranch_vccnz .LBB0_1690
	v_mov_b64_e32 v[76:77], v[242:243]
	v_mov_b64_e32 v[78:79], v[244:245]
	v_mov_b64_e32 v[72:73], v[232:233]
	v_mov_b64_e32 v[74:75], v[234:235]
	s_cbranch_execnz .Lrw_1644_7

; DI float bf2f(unsigned v) { return __uint_as_float(v << 16); }
;   DI void operator()(const f32x4 (&acc)[2][2][4][2], const pg8::Unit& u, int wr, int wc, int fr_, int fq_) const {
;     ...
;             } else if (EPI == EPI_RESID) {
;               if (n == 0) {
;                 const int f8 = u.pn * 256 + bj * 128 + wc * 32 + 8 * fq;
;                 const f32x4 v1 = acc[ai][bj][m][1];
;                 f32x4 r0, r1;
;                 if (rsrc) {
;                   r0 = *(const f32x4*)(rsrc + (size_t)token * 1024 + f8); r1 = *(const f32x4*)(rsrc + (size_t)token * 1024 + f8 + 4);
;                 } else {
;                   const u32x4 xu = *(const u32x4*)(xr + (size_t)token * 1024 + f8);
;                   r0 = (f32x4){bf2f(xu.x & 0xffffu), bf2f(xu.x >> 16), bf2f(xu.y & 0xffffu), bf2f(xu.y >> 16)};
;                   r1 = (f32x4){bf2f(xu.z & 0xffffu), bf2f(xu.z >> 16), bf2f(xu.w & 0xffffu), bf2f(xu.w >> 16)};
;                 }
;                 r0 += v; r1 += v1;
.LBB0_1688:
	s_or_b64 exec, exec, s[34:35]
	v_add_u32_e32 v72, 0x80, v150
	v_ashrrev_i32_e32 v73, 31, v72
	s_waitcnt lgkmcnt(0)
	v_lshlrev_b64 v[64:65], 12, v[72:73]
	v_lshl_add_u64 v[64:65], s[6:7], 0, v[64:65]
	s_and_b64 vcc, exec, s[2:3]
	v_lshl_add_u64 v[76:77], v[148:149], 2, v[64:65]
	s_cbranch_vccnz .LBB0_1691
	v_add_u32_e32 v251, 0x50000, v251
	global_load_dwordx4 v[162:165], v251, s[6:7]
	global_load_dwordx4 v[166:169], v251, s[6:7] offset:16
	global_load_dwordx4 v[170:173], v251, s[6:7] offset:512
	global_load_dwordx4 v[174:177], v251, s[6:7] offset:528
	v_add_u32_e32 v251, 0x10000, v251
	global_load_dwordx4 v[178:181], v251, s[6:7]
	global_load_dwordx4 v[196:199], v251, s[6:7] offset:16
	global_load_dwordx4 v[200:203], v251, s[6:7] offset:512
	global_load_dwordx4 v[204:207], v251, s[6:7] offset:528
	v_add_u32_e32 v251, 0x10000, v251
	global_load_dwordx4 v[208:211], v251, s[6:7]
	global_load_dwordx4 v[212:215], v251, s[6:7] offset:16
	global_load_dwordx4 v[216:219], v251, s[6:7] offset:512
	global_load_dwordx4 v[220:223], v251, s[6:7] offset:528
	v_add_u32_e32 v251, 0x10000, v251
	global_load_dwordx4 v[224:227], v251, s[6:7]
	global_load_dwordx4 v[228:231], v251, s[6:7] offset:16
	global_load_dwordx4 v[232:235], v251, s[6:7] offset:512
	global_load_dwordx4 v[242:245], v251, s[6:7] offset:528
	s_waitcnt vmcnt(0)
	v_mov_b64_e32 v[68:69], v[166:167]
	v_mov_b64_e32 v[70:71], v[168:169]
	v_mov_b64_e32 v[64:65], v[162:163]
	v_mov_b64_e32 v[66:67], v[164:165]
	s_mov_b64 s[34:35], 0
	s_branch .LBB0_1692

; DI float bf2f(unsigned v) { return __uint_as_float(v << 16); }
;   DI void operator()(const f32x4 (&acc)[2][2][4][2], const pg8::Unit& u, int wr, int wc, int fr_, int fq_) const {
;     ...
;             } else if (EPI == EPI_RESID) {
;               if (n == 0) {
;                 const int f8 = u.pn * 256 + bj * 128 + wc * 32 + 8 * fq;
;                 const f32x4 v1 = acc[ai][bj][m][1];
;                 f32x4 r0, r1;
;                 if (rsrc) {
;                   r0 = *(const f32x4*)(rsrc + (size_t)token * 1024 + f8); r1 = *(const f32x4*)(rsrc + (size_t)token * 1024 + f8 + 4);
;                 } else {
;                   const u32x4 xu = *(const u32x4*)(xr + (size_t)token * 1024 + f8);
;                   r0 = (f32x4){bf2f(xu.x & 0xffffu), bf2f(xu.x >> 16), bf2f(xu.y & 0xffffu), bf2f(xu.y >> 16)};
;                   r1 = (f32x4){bf2f(xu.z & 0xffffu), bf2f(xu.z >> 16), bf2f(xu.w & 0xffffu), bf2f(xu.w >> 16)};
;                 }
;                 r0 += v; r1 += v1;
;                 st_bf8(xr + (size_t)token * 1024 + f8, r0, r1, 1.f);
.LBB0_1694:
	v_pk_add_f32 v[66:67], v[62:63], v[66:67]
	v_pk_add_f32 v[78:79], v[60:61], v[64:65]
	v_pk_add_f32 v[64:65], v[58:59], v[70:71]
	v_pk_add_f32 v[68:69], v[56:57], v[68:69]
	v_cvt_pk_bf16_f32 v56, v78, v79
	v_cvt_pk_bf16_f32 v57, v66, v67
	v_cvt_pk_bf16_f32 v58, v68, v69
	v_cvt_pk_bf16_f32 v59, v64, v65
	s_and_b64 vcc, exec, s[2:3]
	global_store_dwordx4 v[74:75], v[56:59], off
	s_cbranch_vccnz .LBB0_1701
	v_mov_b64_e32 v[60:61], v[174:175]
	v_mov_b64_e32 v[62:63], v[176:177]
	v_mov_b64_e32 v[56:57], v[170:171]
	v_mov_b64_e32 v[58:59], v[172:173]
	s_cbranch_execnz .Lrw_1644_9

; DI float bf2f(unsigned v) { return __uint_as_float(v << 16); }
;   DI void operator()(const f32x4 (&acc)[2][2][4][2], const pg8::Unit& u, int wr, int wc, int fr_, int fq_) const {
;     ...
;             } else if (EPI == EPI_RESID) {
;               if (n == 0) {
;                 const int f8 = u.pn * 256 + bj * 128 + wc * 32 + 8 * fq;
;                 const f32x4 v1 = acc[ai][bj][m][1];
;                 f32x4 r0, r1;
;                 if (rsrc) {
;                   r0 = *(const f32x4*)(rsrc + (size_t)token * 1024 + f8); r1 = *(const f32x4*)(rsrc + (size_t)token * 1024 + f8 + 4);
;                 } else {
;                   const u32x4 xu = *(const u32x4*)(xr + (size_t)token * 1024 + f8);
;                   r0 = (f32x4){bf2f(xu.x & 0xffffu), bf2f(xu.x >> 16), bf2f(xu.y & 0xffffu), bf2f(xu.y >> 16)};
;                   r1 = (f32x4){bf2f(xu.z & 0xffffu), bf2f(xu.z >> 16), bf2f(xu.w & 0xffffu), bf2f(xu.w >> 16)};
;                 }
;                 r0 += v; r1 += v1;
.LBB0_1699:
	s_or_b64 exec, exec, s[34:35]
	v_add_u32_e32 v56, 0x90, v150
	v_ashrrev_i32_e32 v57, 31, v56
	s_waitcnt lgkmcnt(0)
	v_lshlrev_b64 v[48:49], 12, v[56:57]
	v_lshl_add_u64 v[48:49], s[6:7], 0, v[48:49]
	s_and_b64 vcc, exec, s[2:3]
	v_lshl_add_u64 v[60:61], v[148:149], 2, v[48:49]
	s_cbranch_vccnz .LBB0_1702
	v_mov_b64_e32 v[52:53], v[196:197]
	v_mov_b64_e32 v[54:55], v[198:199]
	v_mov_b64_e32 v[48:49], v[178:179]
	v_mov_b64_e32 v[50:51], v[180:181]
	s_mov_b64 s[34:35], 0
	s_branch .LBB0_1703

; DI float bf2f(unsigned v) { return __uint_as_float(v << 16); }
;   DI void operator()(const f32x4 (&acc)[2][2][4][2], const pg8::Unit& u, int wr, int wc, int fr_, int fq_) const {
;     ...
;             } else if (EPI == EPI_RESID) {
;               if (n == 0) {
;                 const int f8 = u.pn * 256 + bj * 128 + wc * 32 + 8 * fq;
;                 const f32x4 v1 = acc[ai][bj][m][1];
;                 f32x4 r0, r1;
;                 if (rsrc) {
;                   r0 = *(const f32x4*)(rsrc + (size_t)token * 1024 + f8); r1 = *(const f32x4*)(rsrc + (size_t)token * 1024 + f8 + 4);
;                 } else {
;                   const u32x4 xu = *(const u32x4*)(xr + (size_t)token * 1024 + f8);
;                   r0 = (f32x4){bf2f(xu.x & 0xffffu), bf2f(xu.x >> 16), bf2f(xu.y & 0xffffu), bf2f(xu.y >> 16)};
;                   r1 = (f32x4){bf2f(xu.z & 0xffffu), bf2f(xu.z >> 16), bf2f(xu.w & 0xffffu), bf2f(xu.w >> 16)};
;                 }
;                 r0 += v; r1 += v1;
;                 st_bf8(xr + (size_t)token * 1024 + f8, r0, r1, 1.f);
.LBB0_1705:
	v_pk_add_f32 v[50:51], v[46:47], v[50:51]
	v_pk_add_f32 v[62:63], v[44:45], v[48:49]
	v_pk_add_f32 v[48:49], v[42:43], v[54:55]
	v_pk_add_f32 v[52:53], v[40:41], v[52:53]
	v_cvt_pk_bf16_f32 v40, v62, v63
	v_cvt_pk_bf16_f32 v41, v50, v51
	v_cvt_pk_bf16_f32 v42, v52, v53
	v_cvt_pk_bf16_f32 v43, v48, v49
	s_and_b64 vcc, exec, s[2:3]
	global_store_dwordx4 v[58:59], v[40:43], off
	s_cbranch_vccnz .LBB0_1712
	v_mov_b64_e32 v[44:45], v[204:205]
	v_mov_b64_e32 v[46:47], v[206:207]
	v_mov_b64_e32 v[40:41], v[200:201]
	v_mov_b64_e32 v[42:43], v[202:203]
	s_cbranch_execnz .Lrw_1644_11

; DI float bf2f(unsigned v) { return __uint_as_float(v << 16); }
;   DI void operator()(const f32x4 (&acc)[2][2][4][2], const pg8::Unit& u, int wr, int wc, int fr_, int fq_) const {
;     ...
;             } else if (EPI == EPI_RESID) {
;               if (n == 0) {
;                 const int f8 = u.pn * 256 + bj * 128 + wc * 32 + 8 * fq;
;                 const f32x4 v1 = acc[ai][bj][m][1];
;                 f32x4 r0, r1;
;                 if (rsrc) {
;                   r0 = *(const f32x4*)(rsrc + (size_t)token * 1024 + f8); r1 = *(const f32x4*)(rsrc + (size_t)token * 1024 + f8 + 4);
;                 } else {
;                   const u32x4 xu = *(const u32x4*)(xr + (size_t)token * 1024 + f8);
;                   r0 = (f32x4){bf2f(xu.x & 0xffffu), bf2f(xu.x >> 16), bf2f(xu.y & 0xffffu), bf2f(xu.y >> 16)};
;                   r1 = (f32x4){bf2f(xu.z & 0xffffu), bf2f(xu.z >> 16), bf2f(xu.w & 0xffffu), bf2f(xu.w >> 16)};
;                 }
;                 r0 += v; r1 += v1;
.LBB0_1710:
	s_or_b64 exec, exec, s[34:35]
	v_add_u32_e32 v40, 0xa0, v150
	v_ashrrev_i32_e32 v41, 31, v40
	s_waitcnt lgkmcnt(0)
	v_lshlrev_b64 v[32:33], 12, v[40:41]
	v_lshl_add_u64 v[32:33], s[6:7], 0, v[32:33]
	s_and_b64 vcc, exec, s[2:3]
	v_lshl_add_u64 v[44:45], v[148:149], 2, v[32:33]
	s_cbranch_vccnz .LBB0_1713
	v_mov_b64_e32 v[36:37], v[212:213]
	v_mov_b64_e32 v[38:39], v[214:215]
	v_mov_b64_e32 v[32:33], v[208:209]
	v_mov_b64_e32 v[34:35], v[210:211]
	s_mov_b64 s[34:35], 0
	s_branch .LBB0_1714

; DI float bf2f(unsigned v) { return __uint_as_float(v << 16); }
;   DI void operator()(const f32x4 (&acc)[2][2][4][2], const pg8::Unit& u, int wr, int wc, int fr_, int fq_) const {
;     ...
;             } else if (EPI == EPI_RESID) {
;               if (n == 0) {
;                 const int f8 = u.pn * 256 + bj * 128 + wc * 32 + 8 * fq;
;                 const f32x4 v1 = acc[ai][bj][m][1];
;                 f32x4 r0, r1;
;                 if (rsrc) {
;                   r0 = *(const f32x4*)(rsrc + (size_t)token * 1024 + f8); r1 = *(const f32x4*)(rsrc + (size_t)token * 1024 + f8 + 4);
;                 } else {
;                   const u32x4 xu = *(const u32x4*)(xr + (size_t)token * 1024 + f8);
;                   r0 = (f32x4){bf2f(xu.x & 0xffffu), bf2f(xu.x >> 16), bf2f(xu.y & 0xffffu), bf2f(xu.y >> 16)};
;                   r1 = (f32x4){bf2f(xu.z & 0xffffu), bf2f(xu.z >> 16), bf2f(xu.w & 0xffffu), bf2f(xu.w >> 16)};
;                 }
;                 r0 += v; r1 += v1;
;                 st_bf8(xr + (size_t)token * 1024 + f8, r0, r1, 1.f);
.LBB0_1716:
	v_pk_add_f32 v[34:35], v[30:31], v[34:35]
	v_pk_add_f32 v[46:47], v[28:29], v[32:33]
	v_pk_add_f32 v[32:33], v[26:27], v[38:39]
	v_pk_add_f32 v[36:37], v[24:25], v[36:37]
	v_cvt_pk_bf16_f32 v24, v46, v47
	v_cvt_pk_bf16_f32 v25, v34, v35
	v_cvt_pk_bf16_f32 v26, v36, v37
	v_cvt_pk_bf16_f32 v27, v32, v33
	s_and_b64 vcc, exec, s[2:3]
	global_store_dwordx4 v[42:43], v[24:27], off
	s_cbranch_vccnz .LBB0_1723
	v_mov_b64_e32 v[28:29], v[220:221]
	v_mov_b64_e32 v[30:31], v[222:223]
	v_mov_b64_e32 v[24:25], v[216:217]
	v_mov_b64_e32 v[26:27], v[218:219]
	s_cbranch_execnz .Lrw_1644_13

; DI float bf2f(unsigned v) { return __uint_as_float(v << 16); }
;   DI void operator()(const f32x4 (&acc)[2][2][4][2], const pg8::Unit& u, int wr, int wc, int fr_, int fq_) const {
;     ...
;             } else if (EPI == EPI_RESID) {
;               if (n == 0) {
;                 const int f8 = u.pn * 256 + bj * 128 + wc * 32 + 8 * fq;
;                 const f32x4 v1 = acc[ai][bj][m][1];
;                 f32x4 r0, r1;
;                 if (rsrc) {
;                   r0 = *(const f32x4*)(rsrc + (size_t)token * 1024 + f8); r1 = *(const f32x4*)(rsrc + (size_t)token * 1024 + f8 + 4);
;                 } else {
;                   const u32x4 xu = *(const u32x4*)(xr + (size_t)token * 1024 + f8);
;                   r0 = (f32x4){bf2f(xu.x & 0xffffu), bf2f(xu.x >> 16), bf2f(xu.y & 0xffffu), bf2f(xu.y >> 16)};
;                   r1 = (f32x4){bf2f(xu.z & 0xffffu), bf2f(xu.z >> 16), bf2f(xu.w & 0xffffu), bf2f(xu.w >> 16)};
;                 }
;                 r0 += v; r1 += v1;
.LBB0_1721:
	s_or_b64 exec, exec, s[34:35]
	v_add_u32_e32 v24, 0xb0, v150
	v_ashrrev_i32_e32 v25, 31, v24
	s_waitcnt lgkmcnt(0)
	v_lshlrev_b64 v[16:17], 12, v[24:25]
	v_lshl_add_u64 v[16:17], s[6:7], 0, v[16:17]
	s_and_b64 vcc, exec, s[2:3]
	v_lshl_add_u64 v[28:29], v[148:149], 2, v[16:17]
	s_cbranch_vccnz .LBB0_1724
	v_mov_b64_e32 v[20:21], v[228:229]
	v_mov_b64_e32 v[22:23], v[230:231]
	v_mov_b64_e32 v[16:17], v[224:225]
	v_mov_b64_e32 v[18:19], v[226:227]
	s_mov_b64 s[34:35], 0
	s_branch .LBB0_1725

; DI float bf2f(unsigned v) { return __uint_as_float(v << 16); }
;   DI void operator()(const f32x4 (&acc)[2][2][4][2], const pg8::Unit& u, int wr, int wc, int fr_, int fq_) const {
;     ...
;             } else if (EPI == EPI_RESID) {
;               if (n == 0) {
;                 const int f8 = u.pn * 256 + bj * 128 + wc * 32 + 8 * fq;
;                 const f32x4 v1 = acc[ai][bj][m][1];
;                 f32x4 r0, r1;
;                 if (rsrc) {
;                   r0 = *(const f32x4*)(rsrc + (size_t)token * 1024 + f8); r1 = *(const f32x4*)(rsrc + (size_t)token * 1024 + f8 + 4);
;                 } else {
;                   const u32x4 xu = *(const u32x4*)(xr + (size_t)token * 1024 + f8);
;                   r0 = (f32x4){bf2f(xu.x & 0xffffu), bf2f(xu.x >> 16), bf2f(xu.y & 0xffffu), bf2f(xu.y >> 16)};
;                   r1 = (f32x4){bf2f(xu.z & 0xffffu), bf2f(xu.z >> 16), bf2f(xu.w & 0xffffu), bf2f(xu.w >> 16)};
;                 }
;                 r0 += v; r1 += v1;
;                 st_bf8(xr + (size_t)token * 1024 + f8, r0, r1, 1.f);
.LBB0_1727:
	v_pk_add_f32 v[18:19], v[14:15], v[18:19]
	v_pk_add_f32 v[30:31], v[12:13], v[16:17]
	v_pk_add_f32 v[16:17], v[10:11], v[22:23]
	v_pk_add_f32 v[20:21], v[8:9], v[20:21]
	v_cvt_pk_bf16_f32 v8, v30, v31
	v_cvt_pk_bf16_f32 v9, v18, v19
	v_cvt_pk_bf16_f32 v10, v20, v21
	v_cvt_pk_bf16_f32 v11, v16, v17
	s_and_b64 vcc, exec, s[2:3]
	global_store_dwordx4 v[26:27], v[8:11], off
	s_cbranch_vccnz .LBB0_1732
	v_mov_b64_e32 v[12:13], v[242:243]
	v_mov_b64_e32 v[14:15], v[244:245]
	v_mov_b64_e32 v[8:9], v[232:233]
	v_mov_b64_e32 v[10:11], v[234:235]
	s_cbranch_execnz .Lrw_1644_15
